# mix phase: next-row loads prefetched into v138-v169 before the current row's stores, counted vmcnt(49) wait at loop top
# speedup vs baseline: 1.0010x; 1.0010x over previous
.LBB0_133:
	v_ashrrev_i32_e32 v0, 31, v74
	v_lshrrev_b32_e32 v0, 23, v0
	v_add_lshl_u32 v0, v74, v0, 5
	v_and_b32_e32 v1, 0x1ff, v74
	v_and_b32_e32 v0, 0xffffc000, v0
	v_cmp_ne_u32_e32 vcc, 0, v1
	v_add_u32_e32 v82, v79, v0
	s_mov_b64 s[12:13], 0
	v_cndmask_b32_e64 v83, 0, -1, vcc
	v_mov_b32_e32 v70, v25
	v_mov_b32_e32 v71, v25
	v_mov_b32_e32 v72, v25
	v_mov_b32_e32 v73, v25
	v_mov_b32_e32 v66, v25
	v_mov_b32_e32 v67, v25
	v_mov_b32_e32 v68, v25
	v_mov_b32_e32 v69, v25
	v_mov_b32_e32 v62, v25
	v_mov_b32_e32 v63, v25
	v_mov_b32_e32 v64, v25
	v_mov_b32_e32 v65, v25
	v_mov_b32_e32 v58, v25
	v_mov_b32_e32 v59, v25
	v_mov_b32_e32 v60, v25
	v_mov_b32_e32 v61, v25
	v_mov_b32_e32 v54, v25
	v_mov_b32_e32 v55, v25
	v_mov_b32_e32 v56, v25
	v_mov_b32_e32 v57, v25
	v_mov_b32_e32 v50, v25
	v_mov_b32_e32 v51, v25
	v_mov_b32_e32 v52, v25
	v_mov_b32_e32 v53, v25
	v_mov_b32_e32 v44, v25
	v_mov_b32_e32 v45, v25
	v_mov_b32_e32 v48, v25
	v_mov_b32_e32 v49, v25
	v_mov_b32_e32 v42, v25
	v_mov_b32_e32 v43, v25
	v_mov_b32_e32 v46, v25
	v_mov_b32_e32 v47, v25
	v_add_u32_e32 v170, v80, v83
	v_ashrrev_i32_e32 v171, 31, v170
	v_lshlrev_b64 v[170:171], 13, v[170:171]
	v_lshl_add_u64 v[170:171], v[26:27], 0, v[170:171]
	global_load_dwordx4 v[138:141], v[170:171], off
	global_load_dwordx4 v[142:145], v[170:171], off offset:1024
	global_load_dwordx4 v[146:149], v[170:171], off offset:2048
	global_load_dwordx4 v[150:153], v[170:171], off offset:3072
	v_add_co_u32_e32 v172, vcc, s1, v170
	s_nop 1
	v_addc_co_u32_e32 v173, vcc, 0, v171, vcc
	global_load_dwordx4 v[154:157], v[172:173], off
	global_load_dwordx4 v[158:161], v[172:173], off offset:1024
	global_load_dwordx4 v[162:165], v[172:173], off offset:3072
	global_load_dwordx4 v[166:169], v[172:173], off offset:2048
	s_branch .LBB0_135

.LBB0_135:
	v_add_u32_e32 v30, v80, v83
	v_ashrrev_i32_e32 v31, 31, v30
	v_cmp_lt_i32_e32 vcc, 0, v83
	s_cbranch_vccnz .Lmix_w49
	s_waitcnt vmcnt(0)
	s_branch .Lmix_wd
.Lmix_w49:
	s_waitcnt vmcnt(49)
.Lmix_wd:
	v_mov_b64_e32 v[16:17], v[138:139]
	v_mov_b64_e32 v[18:19], v[140:141]
	v_mov_b64_e32 v[8:9], v[142:143]
	v_mov_b64_e32 v[10:11], v[144:145]
	v_mov_b64_e32 v[32:33], v[146:147]
	v_mov_b64_e32 v[34:35], v[148:149]
	v_mov_b64_e32 v[36:37], v[150:151]
	v_mov_b64_e32 v[38:39], v[152:153]
	v_mov_b64_e32 v[20:21], v[154:155]
	v_mov_b64_e32 v[22:23], v[156:157]
	v_mov_b64_e32 v[12:13], v[158:159]
	v_mov_b64_e32 v[14:15], v[160:161]
	v_mov_b64_e32 v[0:1], v[162:163]
	v_mov_b64_e32 v[2:3], v[164:165]
	v_mov_b64_e32 v[4:5], v[166:167]
	v_mov_b64_e32 v[6:7], v[168:169]
	v_cmp_gt_i32_e32 vcc, 3, v83
	s_cbranch_vccz .Lmix_nopf
	v_add_u32_e32 v170, 1, v30
	v_ashrrev_i32_e32 v171, 31, v170
	v_lshlrev_b64 v[170:171], 13, v[170:171]
	v_lshl_add_u64 v[170:171], v[26:27], 0, v[170:171]
	global_load_dwordx4 v[138:141], v[170:171], off
	global_load_dwordx4 v[142:145], v[170:171], off offset:1024
	global_load_dwordx4 v[146:149], v[170:171], off offset:2048
	global_load_dwordx4 v[150:153], v[170:171], off offset:3072
	v_add_co_u32_e32 v172, vcc, s1, v170
	s_nop 1
	v_addc_co_u32_e32 v173, vcc, 0, v171, vcc
	global_load_dwordx4 v[154:157], v[172:173], off
	global_load_dwordx4 v[158:161], v[172:173], off offset:1024
	global_load_dwordx4 v[162:165], v[172:173], off offset:3072
	global_load_dwordx4 v[166:169], v[172:173], off offset:2048
.Lmix_nopf:
	s_nop 0
	v_mov_b32_e32 v110, v17
	s_nop 0
	v_mov_b32_e32 v111, v9
	v_mov_b32_e32 v114, v19
	v_mov_b32_e32 v115, v11
	v_mov_b32_e32 v40, v16
	v_mov_b32_e32 v41, v8
	v_mov_b32_e32 v112, v18
	v_mov_b32_e32 v113, v10
	s_nop 0
	v_pk_mul_f32 v[116:117], v[34:35], v[34:35]
	v_pk_mul_f32 v[118:119], v[32:33], v[32:33]
	v_pk_mul_f32 v[110:111], v[110:111], v[110:111]
	v_pk_mul_f32 v[114:115], v[114:115], v[114:115]
	v_pk_mov_b32 v[124:125], v[118:119], v[116:117] op_sel:[1,0]
	v_mov_b32_e32 v119, v117
	v_pk_fma_f32 v[40:41], v[40:41], v[40:41], v[110:111]
	v_pk_fma_f32 v[110:111], v[112:113], v[112:113], v[114:115]
	s_nop 0
	v_mul_f32_e32 v120, v37, v37
	v_mul_f32_e32 v122, v39, v39
	v_pk_add_f32 v[112:113], v[124:125], v[118:119]
	v_pk_add_f32 v[40:41], v[40:41], v[110:111]
	v_pk_fma_f32 v[116:117], v[36:37], v[36:37], v[120:121] op_sel_hi:[1,1,0]
	v_pk_fma_f32 v[120:121], v[38:39], v[38:39], v[122:123] op_sel_hi:[1,1,0]
	v_pk_add_f32 v[110:111], v[112:113], v[112:113] op_sel:[0,1] op_sel_hi:[1,0]
	v_pk_add_f32 v[40:41], v[40:41], v[40:41] op_sel:[0,1] op_sel_hi:[1,0]
	ds_read_b128 v[86:89], v77
	ds_read_b128 v[90:93], v77 offset:1024
	ds_read_b128 v[94:97], v82 offset:8192
	ds_read_b128 v[98:101], v82 offset:9216
	ds_read_b128 v[102:105], v82
	ds_read_b128 v[106:109], v82 offset:1024
	s_waitcnt lgkmcnt(3)
	v_pk_add_f32 v[94:95], v[94:95], 1.0 op_sel_hi:[1,0]
	s_waitcnt lgkmcnt(2)
	v_pk_add_f32 v[98:99], v[98:99], 1.0 op_sel_hi:[1,0]
	s_nop 0
	v_mul_f32_e32 v129, v20, v20
	v_mul_f32_e32 v131, v21, v21
	v_mul_f32_e32 v132, v22, v22
	v_mul_f32_e32 v133, v23, v23
	s_nop 0
	v_pk_mul_f32 v[122:123], v[14:15], v[14:15]
	v_pk_mul_f32 v[126:127], v[12:13], v[12:13]
	v_mov_b32_e32 v117, v132
	v_mov_b32_e32 v121, v133
	v_mov_b32_e32 v111, v131
	v_mov_b32_e32 v41, v129
	v_pk_mov_b32 v[114:115], v[126:127], v[122:123] op_sel:[1,0]
	v_mov_b32_e32 v127, v123
	v_pk_add_f32 v[112:113], v[116:117], v[120:121]
	v_pk_add_f32 v[40:41], v[40:41], v[110:111]
	s_nop 0
	v_mul_f32_e32 v128, v5, v5
	v_mul_f32_e32 v130, v7, v7
	v_pk_add_f32 v[114:115], v[114:115], v[126:127]
	v_pk_add_f32 v[40:41], v[40:41], v[112:113]
	v_mul_f32_e32 v134, v0, v0
	v_mul_f32_e32 v135, v1, v1
	v_mul_f32_e32 v136, v2, v2
	v_mul_f32_e32 v137, v3, v3
	v_pk_fma_f32 v[118:119], v[4:5], v[4:5], v[128:129] op_sel_hi:[1,1,0]
	v_pk_fma_f32 v[122:123], v[6:7], v[6:7], v[130:131] op_sel_hi:[1,1,0]
	v_pk_add_f32 v[114:115], v[114:115], v[114:115] op_sel:[0,1] op_sel_hi:[1,0]
	v_pk_add_f32 v[40:41], v[40:41], v[40:41] op_sel:[0,1] op_sel_hi:[1,0]
	v_mov_b32_e32 v119, v136
	v_mov_b32_e32 v123, v137
	v_mov_b32_e32 v115, v135
	v_mov_b32_e32 v41, v134
	v_pk_add_f32 v[116:117], v[118:119], v[122:123]
	v_pk_add_f32 v[40:41], v[40:41], v[114:115]
	s_nop 0
	v_pk_add_f32 v[40:41], v[40:41], v[116:117]
	ds_read_b128 v[110:113], v77 offset:2048
	ds_read_b128 v[114:117], v77 offset:3072
	ds_read_b128 v[118:121], v82 offset:10240
	ds_read_b128 v[122:125], v82 offset:11264
	v_add_f32_e32 v40, v40, v41
	ds_read_b128 v[126:129], v82 offset:2048
	ds_read_b128 v[130:133], v82 offset:3072
	v_add_f32_dpp v40, v40, v40 quad_perm:[1,0,3,2] row_mask:0xf bank_mask:0xf bound_ctrl:1
	s_waitcnt lgkmcnt(3)
	v_pk_add_f32 v[118:119], v[118:119], 1.0 op_sel_hi:[1,0]
	v_add_f32_dpp v40, v40, v40 quad_perm:[2,3,0,1] row_mask:0xf bank_mask:0xf bound_ctrl:1
	s_nop 1
	v_add_f32_dpp v40, v40, v40 row_half_mirror row_mask:0xf bank_mask:0xf bound_ctrl:1
	s_nop 1
	v_add_f32_dpp v40, v40, v40 row_mirror row_mask:0xf bank_mask:0xf bound_ctrl:1
	ds_bpermute_b32 v41, v75, v40
	s_waitcnt lgkmcnt(0)
	v_add_f32_e32 v134, v40, v41
	ds_bpermute_b32 v135, v76, v134
	v_pk_add_f32 v[40:41], v[96:97], 1.0 op_sel_hi:[1,0]
	v_pk_add_f32 v[96:97], v[100:101], 1.0 op_sel_hi:[1,0]
	s_waitcnt lgkmcnt(0)
	v_add_f32_e32 v100, v134, v135
	v_fmamk_f32 v100, v100, 0x3a000000, v81
	v_mul_f32_e32 v101, 0x4b800000, v100
	v_cmp_gt_f32_e32 vcc, s3, v100
	s_nop 1
	v_cndmask_b32_e32 v100, v100, v101, vcc
	v_rsq_f32_e32 v134, v100
	v_pk_add_f32 v[100:101], v[120:121], 1.0 op_sel_hi:[1,0]
	v_mul_f32_e32 v120, 0x45800000, v134
	v_cndmask_b32_e32 v120, v134, v120, vcc
	v_pk_mul_f32 v[18:19], v[18:19], v[120:121] op_sel_hi:[1,0]
	v_pk_mul_f32 v[16:17], v[16:17], v[120:121] op_sel_hi:[1,0]
	v_pk_mul_f32 v[8:9], v[8:9], v[120:121] op_sel_hi:[1,0]
	v_pk_mul_f32 v[10:11], v[10:11], v[120:121] op_sel_hi:[1,0]
	v_pk_mul_f32 v[32:33], v[32:33], v[120:121] op_sel_hi:[1,0]
	v_pk_mul_f32 v[16:17], v[86:87], v[16:17]
	v_pk_mul_f32 v[18:19], v[88:89], v[18:19]
	v_pk_mul_f32 v[86:87], v[90:91], v[8:9]
	v_pk_mul_f32 v[38:39], v[38:39], v[120:121] op_sel_hi:[1,0]
	v_pk_mul_f32 v[36:37], v[36:37], v[120:121] op_sel_hi:[1,0]
	v_pk_mul_f32 v[34:35], v[34:35], v[120:121] op_sel_hi:[1,0]
	v_pk_mul_f32 v[88:89], v[92:93], v[10:11]
	v_pk_mul_f32 v[90:91], v[110:111], v[32:33]
	v_pk_fma_f32 v[8:9], v[40:41], v[18:19], v[104:105]
	v_pk_fma_f32 v[18:19], v[98:99], v[86:87], v[106:107]
	v_pk_mul_f32 v[40:41], v[114:115], v[36:37]
	v_pk_mul_f32 v[36:37], v[116:117], v[38:39]
	v_pk_add_f32 v[38:39], v[124:125], 1.0 op_sel_hi:[1,0]
	v_pk_add_f32 v[86:87], v[122:123], 1.0 op_sel_hi:[1,0]
	v_pk_mul_f32 v[32:33], v[112:113], v[34:35]
	v_pk_fma_f32 v[10:11], v[94:95], v[16:17], v[102:103]
	v_pk_fma_f32 v[16:17], v[96:97], v[88:89], v[108:109]
	v_pk_fma_f32 v[34:35], v[118:119], v[90:91], v[126:127]
	v_pk_fma_f32 v[36:37], v[38:39], v[36:37], v[132:133]
	v_pk_fma_f32 v[38:39], v[86:87], v[40:41], v[130:131]
	ds_read_b128 v[86:89], v77 offset:4096
	ds_read_b128 v[90:93], v82 offset:12288
	ds_read_b128 v[94:97], v82 offset:4096
	v_pk_mul_f32 v[22:23], v[22:23], v[120:121] op_sel_hi:[1,0]
	v_pk_mul_f32 v[20:21], v[20:21], v[120:121] op_sel_hi:[1,0]
	v_pk_fma_f32 v[32:33], v[100:101], v[32:33], v[128:129]
	ds_read_b128 v[98:101], v77 offset:5120
	s_waitcnt lgkmcnt(3)
	v_pk_mul_f32 v[40:41], v[86:87], v[20:21]
	v_pk_mul_f32 v[20:21], v[88:89], v[22:23]
	ds_read_b128 v[86:89], v82 offset:13312
	s_waitcnt lgkmcnt(3)
	v_pk_add_f32 v[22:23], v[92:93], 1.0 op_sel_hi:[1,0]
	v_pk_add_f32 v[102:103], v[90:91], 1.0 op_sel_hi:[1,0]
	ds_read_b128 v[90:93], v82 offset:5120
	v_pk_mul_f32 v[14:15], v[14:15], v[120:121] op_sel_hi:[1,0]
	v_pk_mul_f32 v[12:13], v[12:13], v[120:121] op_sel_hi:[1,0]
	s_waitcnt lgkmcnt(3)
	v_pk_fma_f32 v[20:21], v[22:23], v[20:21], v[96:97]
	v_pk_fma_f32 v[22:23], v[102:103], v[40:41], v[94:95]
	s_waitcnt lgkmcnt(2)
	v_pk_mul_f32 v[40:41], v[12:13], v[98:99]
	v_pk_mul_f32 v[12:13], v[14:15], v[100:101]
	s_waitcnt lgkmcnt(1)
	v_pk_add_f32 v[14:15], v[88:89], 1.0 op_sel_hi:[1,0]
	v_pk_add_f32 v[86:87], v[86:87], 1.0 op_sel_hi:[1,0]
	s_waitcnt lgkmcnt(0)
	v_pk_fma_f32 v[12:13], v[12:13], v[14:15], v[92:93]
	v_pk_fma_f32 v[14:15], v[40:41], v[86:87], v[90:91]
	ds_read_b128 v[86:89], v77 offset:6144
	ds_read_b128 v[90:93], v82 offset:14336
	ds_read_b128 v[94:97], v82 offset:6144
	v_pk_mul_f32 v[6:7], v[6:7], v[120:121] op_sel_hi:[1,0]
	v_pk_mul_f32 v[4:5], v[4:5], v[120:121] op_sel_hi:[1,0]
	ds_read_b128 v[98:101], v77 offset:7168
	s_waitcnt lgkmcnt(3)
	v_pk_mul_f32 v[40:41], v[4:5], v[86:87]
	v_pk_mul_f32 v[4:5], v[6:7], v[88:89]
	ds_read_b128 v[86:89], v82 offset:15360
	s_waitcnt lgkmcnt(3)
	v_pk_add_f32 v[6:7], v[92:93], 1.0 op_sel_hi:[1,0]
	v_pk_add_f32 v[102:103], v[90:91], 1.0 op_sel_hi:[1,0]
	ds_read_b128 v[90:93], v82 offset:7168
	v_pk_mul_f32 v[2:3], v[2:3], v[120:121] op_sel_hi:[1,0]
	v_pk_mul_f32 v[0:1], v[0:1], v[120:121] op_sel_hi:[1,0]
	s_waitcnt lgkmcnt(3)
	v_pk_fma_f32 v[4:5], v[4:5], v[6:7], v[96:97]
	v_pk_fma_f32 v[6:7], v[40:41], v[102:103], v[94:95]
	s_waitcnt lgkmcnt(2)
	v_pk_mul_f32 v[40:41], v[0:1], v[98:99]
	v_pk_mul_f32 v[0:1], v[2:3], v[100:101]
	s_waitcnt lgkmcnt(1)
	v_pk_add_f32 v[2:3], v[88:89], 1.0 op_sel_hi:[1,0]
	v_pk_add_f32 v[86:87], v[86:87], 1.0 op_sel_hi:[1,0]
	s_waitcnt lgkmcnt(0)
	v_pk_fma_f32 v[0:1], v[0:1], v[2:3], v[92:93]
	v_pk_fma_f32 v[2:3], v[40:41], v[86:87], v[90:91]
	v_cmp_lt_i32_e32 vcc, -1, v83
	s_and_saveexec_b64 s[14:15], vcc
	s_cbranch_execz .LBB0_134
	ds_read_b128 v[86:89], v78
	v_sub_f32_e32 v43, v43, v11
	v_sub_f32_e32 v42, v42, v10
	v_lshlrev_b64 v[40:41], 12, v[30:31]
	v_sub_f32_e32 v47, v47, v9
	v_sub_f32_e32 v46, v46, v8
	s_waitcnt lgkmcnt(0)
	v_pk_fma_f32 v[86:87], v[42:43], v[86:87], v[10:11]
	v_lshl_add_u64 v[40:41], v[28:29], 0, v[40:41]
	v_pk_fma_f32 v[88:89], v[46:47], v[88:89], v[8:9]
	v_cvt_pk_bf16_f32 v86, v86, v87
	v_sub_f32_e32 v45, v45, v19
	v_cvt_pk_bf16_f32 v87, v88, v89
	global_store_dwordx2 v[40:41], v[86:87], off
	ds_read_b128 v[86:89], v78 offset:1024
	v_sub_f32_e32 v44, v44, v18
	v_sub_f32_e32 v49, v49, v17
	v_sub_f32_e32 v48, v48, v16
	v_sub_f32_e32 v51, v51, v35
	s_waitcnt lgkmcnt(0)
	v_pk_fma_f32 v[86:87], v[44:45], v[86:87], v[18:19]
	v_pk_fma_f32 v[88:89], v[48:49], v[88:89], v[16:17]
	v_cvt_pk_bf16_f32 v86, v86, v87
	v_sub_f32_e32 v50, v50, v34
	v_cvt_pk_bf16_f32 v87, v88, v89
	global_store_dwordx2 v[40:41], v[86:87], off offset:512
	ds_read_b128 v[86:89], v78 offset:2048
	v_sub_f32_e32 v53, v53, v33
	v_sub_f32_e32 v52, v52, v32
	v_sub_f32_e32 v55, v55, v39
	v_sub_f32_e32 v54, v54, v38
	s_waitcnt lgkmcnt(0)
	v_pk_fma_f32 v[86:87], v[50:51], v[86:87], v[34:35]
	v_pk_fma_f32 v[88:89], v[52:53], v[88:89], v[32:33]
	v_cvt_pk_bf16_f32 v86, v86, v87
	v_sub_f32_e32 v57, v57, v37
	v_cvt_pk_bf16_f32 v87, v88, v89
	global_store_dwordx2 v[40:41], v[86:87], off offset:1024
	ds_read_b128 v[86:89], v78 offset:3072
	v_sub_f32_e32 v56, v56, v36
	v_sub_f32_e32 v59, v59, v23
	v_sub_f32_e32 v58, v58, v22
	v_sub_f32_e32 v61, v61, v21
	s_waitcnt lgkmcnt(0)
	v_pk_fma_f32 v[86:87], v[54:55], v[86:87], v[38:39]
	v_pk_fma_f32 v[88:89], v[56:57], v[88:89], v[36:37]
	v_cvt_pk_bf16_f32 v86, v86, v87
	v_sub_f32_e32 v60, v60, v20
	v_cvt_pk_bf16_f32 v87, v88, v89
	global_store_dwordx2 v[40:41], v[86:87], off offset:1536
	ds_read_b128 v[86:89], v78 offset:4096
	v_sub_f32_e32 v63, v63, v15
	v_sub_f32_e32 v62, v62, v14
	v_sub_f32_e32 v65, v65, v13
	v_sub_f32_e32 v64, v64, v12
	s_waitcnt lgkmcnt(0)
	v_pk_fma_f32 v[86:87], v[58:59], v[86:87], v[22:23]
	v_pk_fma_f32 v[88:89], v[60:61], v[88:89], v[20:21]
	v_cvt_pk_bf16_f32 v86, v86, v87
	v_sub_f32_e32 v67, v67, v7
	v_cvt_pk_bf16_f32 v87, v88, v89
	global_store_dwordx2 v[40:41], v[86:87], off offset:2048
	ds_read_b128 v[86:89], v78 offset:5120
	v_sub_f32_e32 v66, v66, v6
	v_sub_f32_e32 v69, v69, v5
	v_sub_f32_e32 v68, v68, v4
	v_sub_f32_e32 v71, v71, v3
	s_waitcnt lgkmcnt(0)
	v_pk_fma_f32 v[86:87], v[62:63], v[86:87], v[14:15]
	v_pk_fma_f32 v[88:89], v[64:65], v[88:89], v[12:13]
	v_cvt_pk_bf16_f32 v86, v86, v87
	v_sub_f32_e32 v70, v70, v2
	v_cvt_pk_bf16_f32 v87, v88, v89
	global_store_dwordx2 v[40:41], v[86:87], off offset:2560
	ds_read_b128 v[86:89], v78 offset:6144
	v_sub_f32_e32 v73, v73, v1
	v_sub_f32_e32 v72, v72, v0
	v_add_co_u32_e32 v92, vcc, s16, v40
	s_waitcnt lgkmcnt(0)
	v_pk_fma_f32 v[86:87], v[66:67], v[86:87], v[6:7]
	v_pk_fma_f32 v[88:89], v[68:69], v[88:89], v[4:5]
	v_cvt_pk_bf16_f32 v86, v86, v87
	v_addc_co_u32_e32 v93, vcc, 0, v41, vcc
	v_cvt_pk_bf16_f32 v87, v88, v89
	global_store_dwordx2 v[40:41], v[86:87], off offset:3072
	ds_read_b128 v[86:89], v78 offset:7168
	s_waitcnt lgkmcnt(0)
	v_pk_fma_f32 v[86:87], v[70:71], v[86:87], v[2:3]
	v_pk_fma_f32 v[88:89], v[72:73], v[88:89], v[0:1]
	v_cvt_pk_bf16_f32 v86, v86, v87
	s_nop 0
	v_cvt_pk_bf16_f32 v87, v88, v89
	global_store_dwordx2 v[40:41], v[86:87], off offset:3584
	ds_read_b128 v[86:89], v78 offset:8192
	s_waitcnt lgkmcnt(0)
	v_pk_fma_f32 v[88:89], v[46:47], v[88:89], v[8:9]
	v_pk_fma_f32 v[86:87], v[42:43], v[86:87], v[10:11]
	s_nop 0
	v_cvt_pk_bf16_f32 v90, v86, v87
	v_cvt_pk_bf16_f32 v91, v88, v89
	ds_read_b128 v[86:89], v78 offset:9216
	global_store_dwordx2 v[92:93], v[90:91], off
	s_waitcnt lgkmcnt(0)
	v_pk_fma_f32 v[88:89], v[48:49], v[88:89], v[16:17]
	v_pk_fma_f32 v[86:87], v[44:45], v[86:87], v[18:19]
	s_nop 0
	v_cvt_pk_bf16_f32 v90, v86, v87
	v_cvt_pk_bf16_f32 v91, v88, v89
	ds_read_b128 v[86:89], v78 offset:10240
	global_store_dwordx2 v[92:93], v[90:91], off offset:512
	s_waitcnt lgkmcnt(0)
	v_pk_fma_f32 v[88:89], v[52:53], v[88:89], v[32:33]
	v_pk_fma_f32 v[86:87], v[50:51], v[86:87], v[34:35]
	s_nop 0
	v_cvt_pk_bf16_f32 v90, v86, v87
	v_cvt_pk_bf16_f32 v91, v88, v89
	ds_read_b128 v[86:89], v78 offset:11264
	global_store_dwordx2 v[92:93], v[90:91], off offset:1024
	s_waitcnt lgkmcnt(0)
	v_pk_fma_f32 v[88:89], v[56:57], v[88:89], v[36:37]
	v_pk_fma_f32 v[86:87], v[54:55], v[86:87], v[38:39]
	s_nop 0
	v_cvt_pk_bf16_f32 v90, v86, v87
	v_cvt_pk_bf16_f32 v91, v88, v89
	ds_read_b128 v[86:89], v78 offset:12288
	global_store_dwordx2 v[92:93], v[90:91], off offset:1536
	s_waitcnt lgkmcnt(0)
	v_pk_fma_f32 v[88:89], v[60:61], v[88:89], v[20:21]
	v_pk_fma_f32 v[86:87], v[58:59], v[86:87], v[22:23]
	s_nop 0
	v_cvt_pk_bf16_f32 v90, v86, v87
	v_cvt_pk_bf16_f32 v91, v88, v89
	ds_read_b128 v[86:89], v78 offset:13312
	global_store_dwordx2 v[92:93], v[90:91], off offset:2048
	s_waitcnt lgkmcnt(0)
	v_pk_fma_f32 v[88:89], v[64:65], v[88:89], v[12:13]
	v_pk_fma_f32 v[86:87], v[62:63], v[86:87], v[14:15]
	s_nop 0
	v_cvt_pk_bf16_f32 v90, v86, v87
	v_cvt_pk_bf16_f32 v91, v88, v89
	ds_read_b128 v[86:89], v78 offset:14336
	global_store_dwordx2 v[92:93], v[90:91], off offset:2560
	s_waitcnt lgkmcnt(0)
	v_pk_fma_f32 v[88:89], v[68:69], v[88:89], v[4:5]
	v_pk_fma_f32 v[86:87], v[66:67], v[86:87], v[6:7]
	s_nop 0
	v_cvt_pk_bf16_f32 v90, v86, v87
	v_cvt_pk_bf16_f32 v91, v88, v89
	ds_read_b128 v[86:89], v78 offset:15360
	global_store_dwordx2 v[92:93], v[90:91], off offset:3072
	s_waitcnt lgkmcnt(0)
	v_pk_fma_f32 v[86:87], v[70:71], v[86:87], v[2:3]
	v_pk_fma_f32 v[88:89], v[72:73], v[88:89], v[0:1]
	v_cvt_pk_bf16_f32 v86, v86, v87
	s_nop 0
	v_cvt_pk_bf16_f32 v87, v88, v89
	global_store_dwordx2 v[92:93], v[86:87], off offset:3584
	ds_read_b128 v[86:89], v78 offset:16384
	v_add_co_u32_e32 v92, vcc, s17, v40
	s_waitcnt lgkmcnt(0)
	v_pk_fma_f32 v[88:89], v[46:47], v[88:89], v[8:9]
	v_pk_fma_f32 v[86:87], v[42:43], v[86:87], v[10:11]
	v_addc_co_u32_e32 v93, vcc, 0, v41, vcc
	v_cvt_pk_bf16_f32 v90, v86, v87
	v_cvt_pk_bf16_f32 v91, v88, v89
	ds_read_b128 v[86:89], v78 offset:17408
	global_store_dwordx2 v[92:93], v[90:91], off
	s_waitcnt lgkmcnt(0)
	v_pk_fma_f32 v[88:89], v[48:49], v[88:89], v[16:17]
	v_pk_fma_f32 v[86:87], v[44:45], v[86:87], v[18:19]
	s_nop 0
	v_cvt_pk_bf16_f32 v90, v86, v87
	v_cvt_pk_bf16_f32 v91, v88, v89
	ds_read_b128 v[86:89], v78 offset:18432
	global_store_dwordx2 v[92:93], v[90:91], off offset:512
	s_waitcnt lgkmcnt(0)
	v_pk_fma_f32 v[88:89], v[52:53], v[88:89], v[32:33]
	v_pk_fma_f32 v[86:87], v[50:51], v[86:87], v[34:35]
	s_nop 0
	v_cvt_pk_bf16_f32 v90, v86, v87
	v_cvt_pk_bf16_f32 v91, v88, v89
	ds_read_b128 v[86:89], v78 offset:19456
	global_store_dwordx2 v[92:93], v[90:91], off offset:1024
	s_waitcnt lgkmcnt(0)
	v_pk_fma_f32 v[88:89], v[56:57], v[88:89], v[36:37]
	v_pk_fma_f32 v[86:87], v[54:55], v[86:87], v[38:39]
	s_nop 0
	v_cvt_pk_bf16_f32 v90, v86, v87
	v_cvt_pk_bf16_f32 v91, v88, v89
	ds_read_b128 v[86:89], v78 offset:20480
	global_store_dwordx2 v[92:93], v[90:91], off offset:1536
	s_waitcnt lgkmcnt(0)
	v_pk_fma_f32 v[88:89], v[60:61], v[88:89], v[20:21]
	v_pk_fma_f32 v[86:87], v[58:59], v[86:87], v[22:23]
	s_nop 0
	v_cvt_pk_bf16_f32 v90, v86, v87
	v_cvt_pk_bf16_f32 v91, v88, v89
	ds_read_b128 v[86:89], v78 offset:21504
	global_store_dwordx2 v[92:93], v[90:91], off offset:2048
	s_waitcnt lgkmcnt(0)
	v_pk_fma_f32 v[88:89], v[64:65], v[88:89], v[12:13]
	v_pk_fma_f32 v[86:87], v[62:63], v[86:87], v[14:15]
	s_nop 0
	v_cvt_pk_bf16_f32 v90, v86, v87
	v_cvt_pk_bf16_f32 v91, v88, v89
	ds_read_b128 v[86:89], v78 offset:22528
	global_store_dwordx2 v[92:93], v[90:91], off offset:2560
	s_waitcnt lgkmcnt(0)
	v_pk_fma_f32 v[88:89], v[68:69], v[88:89], v[4:5]
	v_pk_fma_f32 v[86:87], v[66:67], v[86:87], v[6:7]
	s_nop 0
	v_cvt_pk_bf16_f32 v90, v86, v87
	v_cvt_pk_bf16_f32 v91, v88, v89
	ds_read_b128 v[86:89], v78 offset:23552
	global_store_dwordx2 v[92:93], v[90:91], off offset:3072
	s_waitcnt lgkmcnt(0)
	v_pk_fma_f32 v[86:87], v[70:71], v[86:87], v[2:3]
	v_pk_fma_f32 v[88:89], v[72:73], v[88:89], v[0:1]
	v_cvt_pk_bf16_f32 v86, v86, v87
	s_nop 0
	v_cvt_pk_bf16_f32 v87, v88, v89
	global_store_dwordx2 v[92:93], v[86:87], off offset:3584
	ds_read_b128 v[86:89], v78 offset:24576
	v_add_co_u32_e32 v92, vcc, s18, v40
	s_waitcnt lgkmcnt(0)
	v_pk_fma_f32 v[88:89], v[46:47], v[88:89], v[8:9]
	v_pk_fma_f32 v[86:87], v[42:43], v[86:87], v[10:11]
	v_addc_co_u32_e32 v93, vcc, 0, v41, vcc
	v_cvt_pk_bf16_f32 v90, v86, v87
	v_cvt_pk_bf16_f32 v91, v88, v89
	ds_read_b128 v[86:89], v78 offset:25600
	global_store_dwordx2 v[92:93], v[90:91], off
	s_waitcnt lgkmcnt(0)
	v_pk_fma_f32 v[88:89], v[48:49], v[88:89], v[16:17]
	v_pk_fma_f32 v[86:87], v[44:45], v[86:87], v[18:19]
	s_nop 0
	v_cvt_pk_bf16_f32 v90, v86, v87
	v_cvt_pk_bf16_f32 v91, v88, v89
	ds_read_b128 v[86:89], v78 offset:26624
	global_store_dwordx2 v[92:93], v[90:91], off offset:512
	s_waitcnt lgkmcnt(0)
	v_pk_fma_f32 v[88:89], v[52:53], v[88:89], v[32:33]
	v_pk_fma_f32 v[86:87], v[50:51], v[86:87], v[34:35]
	s_nop 0
	v_cvt_pk_bf16_f32 v90, v86, v87
	v_cvt_pk_bf16_f32 v91, v88, v89
	ds_read_b128 v[86:89], v78 offset:27648
	global_store_dwordx2 v[92:93], v[90:91], off offset:1024
	s_waitcnt lgkmcnt(0)
	v_pk_fma_f32 v[88:89], v[56:57], v[88:89], v[36:37]
	v_pk_fma_f32 v[86:87], v[54:55], v[86:87], v[38:39]
	s_nop 0
	v_cvt_pk_bf16_f32 v90, v86, v87
	v_cvt_pk_bf16_f32 v91, v88, v89
	ds_read_b128 v[86:89], v78 offset:28672
	global_store_dwordx2 v[92:93], v[90:91], off offset:1536
	s_waitcnt lgkmcnt(0)
	v_pk_fma_f32 v[88:89], v[60:61], v[88:89], v[20:21]
	v_pk_fma_f32 v[86:87], v[58:59], v[86:87], v[22:23]
	s_nop 0
	v_cvt_pk_bf16_f32 v90, v86, v87
	v_cvt_pk_bf16_f32 v91, v88, v89
	ds_read_b128 v[86:89], v78 offset:29696
	global_store_dwordx2 v[92:93], v[90:91], off offset:2048
	s_waitcnt lgkmcnt(0)
	v_pk_fma_f32 v[88:89], v[64:65], v[88:89], v[12:13]
	v_pk_fma_f32 v[86:87], v[62:63], v[86:87], v[14:15]
	s_nop 0
	v_cvt_pk_bf16_f32 v90, v86, v87
	v_cvt_pk_bf16_f32 v91, v88, v89
	ds_read_b128 v[86:89], v78 offset:30720
	global_store_dwordx2 v[92:93], v[90:91], off offset:2560
	s_waitcnt lgkmcnt(0)
	v_pk_fma_f32 v[88:89], v[68:69], v[88:89], v[4:5]
	v_pk_fma_f32 v[86:87], v[66:67], v[86:87], v[6:7]
	s_nop 0
	v_cvt_pk_bf16_f32 v90, v86, v87
	v_cvt_pk_bf16_f32 v91, v88, v89
	ds_read_b128 v[86:89], v78 offset:31744
	global_store_dwordx2 v[92:93], v[90:91], off offset:3072
	s_waitcnt lgkmcnt(0)
	v_pk_fma_f32 v[86:87], v[70:71], v[86:87], v[2:3]
	v_pk_fma_f32 v[88:89], v[72:73], v[88:89], v[0:1]
	v_cvt_pk_bf16_f32 v86, v86, v87
	s_nop 0
	v_cvt_pk_bf16_f32 v87, v88, v89
	global_store_dwordx2 v[92:93], v[86:87], off offset:3584
	ds_read_b128 v[86:89], v78 offset:32768
	v_add_co_u32_e32 v92, vcc, s19, v40
	s_waitcnt lgkmcnt(0)
	v_pk_fma_f32 v[88:89], v[46:47], v[88:89], v[8:9]
	v_pk_fma_f32 v[86:87], v[42:43], v[86:87], v[10:11]
	v_addc_co_u32_e32 v93, vcc, 0, v41, vcc
	v_cvt_pk_bf16_f32 v90, v86, v87
	v_cvt_pk_bf16_f32 v91, v88, v89
	ds_read_b128 v[86:89], v78 offset:33792
	global_store_dwordx2 v[92:93], v[90:91], off
	s_waitcnt lgkmcnt(0)
	v_pk_fma_f32 v[88:89], v[48:49], v[88:89], v[16:17]
	v_pk_fma_f32 v[86:87], v[44:45], v[86:87], v[18:19]
	s_nop 0
	v_cvt_pk_bf16_f32 v90, v86, v87
	v_cvt_pk_bf16_f32 v91, v88, v89
	ds_read_b128 v[86:89], v78 offset:34816
	global_store_dwordx2 v[92:93], v[90:91], off offset:512
	s_waitcnt lgkmcnt(0)
	v_pk_fma_f32 v[88:89], v[52:53], v[88:89], v[32:33]
	v_pk_fma_f32 v[86:87], v[50:51], v[86:87], v[34:35]
	s_nop 0
	v_cvt_pk_bf16_f32 v90, v86, v87
	v_cvt_pk_bf16_f32 v91, v88, v89
	ds_read_b128 v[86:89], v78 offset:35840
	global_store_dwordx2 v[92:93], v[90:91], off offset:1024
	s_waitcnt lgkmcnt(0)
	v_pk_fma_f32 v[88:89], v[56:57], v[88:89], v[36:37]
	v_pk_fma_f32 v[86:87], v[54:55], v[86:87], v[38:39]
	s_nop 0
	v_cvt_pk_bf16_f32 v90, v86, v87
	v_cvt_pk_bf16_f32 v91, v88, v89
	ds_read_b128 v[86:89], v78 offset:36864
	global_store_dwordx2 v[92:93], v[90:91], off offset:1536
	s_waitcnt lgkmcnt(0)
	v_pk_fma_f32 v[88:89], v[60:61], v[88:89], v[20:21]
	v_pk_fma_f32 v[86:87], v[58:59], v[86:87], v[22:23]
	s_nop 0
	v_cvt_pk_bf16_f32 v90, v86, v87
	v_cvt_pk_bf16_f32 v91, v88, v89
	ds_read_b128 v[86:89], v78 offset:37888
	global_store_dwordx2 v[92:93], v[90:91], off offset:2048
	s_waitcnt lgkmcnt(0)
	v_pk_fma_f32 v[88:89], v[64:65], v[88:89], v[12:13]
	v_pk_fma_f32 v[86:87], v[62:63], v[86:87], v[14:15]
	s_nop 0
	v_cvt_pk_bf16_f32 v90, v86, v87
	v_cvt_pk_bf16_f32 v91, v88, v89
	ds_read_b128 v[86:89], v78 offset:38912
	global_store_dwordx2 v[92:93], v[90:91], off offset:2560
	s_waitcnt lgkmcnt(0)
	v_pk_fma_f32 v[88:89], v[68:69], v[88:89], v[4:5]
	v_pk_fma_f32 v[86:87], v[66:67], v[86:87], v[6:7]
	s_nop 0
	v_cvt_pk_bf16_f32 v90, v86, v87
	v_cvt_pk_bf16_f32 v91, v88, v89
	ds_read_b128 v[86:89], v78 offset:39936
	global_store_dwordx2 v[92:93], v[90:91], off offset:3072
	s_waitcnt lgkmcnt(0)
	v_pk_fma_f32 v[86:87], v[70:71], v[86:87], v[2:3]
	v_pk_fma_f32 v[88:89], v[72:73], v[88:89], v[0:1]
	v_cvt_pk_bf16_f32 v86, v86, v87
	s_nop 0
	v_cvt_pk_bf16_f32 v87, v88, v89
	global_store_dwordx2 v[92:93], v[86:87], off offset:3584
	ds_read_b128 v[86:89], v78 offset:40960
	s_waitcnt lgkmcnt(0)
	v_pk_fma_f32 v[42:43], v[42:43], v[86:87], v[10:11]
	v_pk_fma_f32 v[46:47], v[46:47], v[88:89], v[8:9]
	v_cvt_pk_bf16_f32 v42, v42, v43
	s_nop 0
	v_cvt_pk_bf16_f32 v43, v46, v47
	ds_read_b128 v[86:89], v78 offset:41984
	v_add_co_u32_e32 v46, vcc, s20, v40
	s_nop 1
	v_addc_co_u32_e32 v47, vcc, 0, v41, vcc
	global_store_dwordx2 v[46:47], v[42:43], off
	s_waitcnt lgkmcnt(0)
	v_pk_fma_f32 v[40:41], v[48:49], v[88:89], v[16:17]
	v_pk_fma_f32 v[42:43], v[44:45], v[86:87], v[18:19]
	s_nop 0
	v_cvt_pk_bf16_f32 v44, v42, v43
	v_cvt_pk_bf16_f32 v45, v40, v41
	ds_read_b128 v[40:43], v78 offset:43008
	global_store_dwordx2 v[46:47], v[44:45], off offset:512
	s_waitcnt lgkmcnt(0)
	v_pk_fma_f32 v[42:43], v[52:53], v[42:43], v[32:33]
	v_pk_fma_f32 v[40:41], v[50:51], v[40:41], v[34:35]
	s_nop 0
	v_cvt_pk_bf16_f32 v44, v40, v41
	v_cvt_pk_bf16_f32 v45, v42, v43
	ds_read_b128 v[40:43], v78 offset:44032
	global_store_dwordx2 v[46:47], v[44:45], off offset:1024
	s_waitcnt lgkmcnt(0)
	v_pk_fma_f32 v[42:43], v[56:57], v[42:43], v[36:37]
	v_pk_fma_f32 v[40:41], v[54:55], v[40:41], v[38:39]
	s_nop 0
	v_cvt_pk_bf16_f32 v44, v40, v41
	v_cvt_pk_bf16_f32 v45, v42, v43
	ds_read_b128 v[40:43], v78 offset:45056
	global_store_dwordx2 v[46:47], v[44:45], off offset:1536
	s_waitcnt lgkmcnt(0)
	v_pk_fma_f32 v[42:43], v[60:61], v[42:43], v[20:21]
	v_pk_fma_f32 v[40:41], v[58:59], v[40:41], v[22:23]
	s_nop 0
	v_cvt_pk_bf16_f32 v44, v40, v41
	v_cvt_pk_bf16_f32 v45, v42, v43
	ds_read_b128 v[40:43], v78 offset:46080
	global_store_dwordx2 v[46:47], v[44:45], off offset:2048
	s_waitcnt lgkmcnt(0)
	v_pk_fma_f32 v[42:43], v[64:65], v[42:43], v[12:13]
	v_pk_fma_f32 v[40:41], v[62:63], v[40:41], v[14:15]
	s_nop 0
	v_cvt_pk_bf16_f32 v44, v40, v41
	v_cvt_pk_bf16_f32 v45, v42, v43
	ds_read_b128 v[40:43], v78 offset:47104
	global_store_dwordx2 v[46:47], v[44:45], off offset:2560
	s_waitcnt lgkmcnt(0)
	v_pk_fma_f32 v[42:43], v[68:69], v[42:43], v[4:5]
	v_pk_fma_f32 v[40:41], v[66:67], v[40:41], v[6:7]
	s_nop 0
	v_cvt_pk_bf16_f32 v44, v40, v41
	v_cvt_pk_bf16_f32 v45, v42, v43
	ds_read_b128 v[40:43], v78 offset:48128
	global_store_dwordx2 v[46:47], v[44:45], off offset:3072
	s_waitcnt lgkmcnt(0)
	v_pk_fma_f32 v[40:41], v[70:71], v[40:41], v[2:3]
	v_pk_fma_f32 v[42:43], v[72:73], v[42:43], v[0:1]
	v_cvt_pk_bf16_f32 v40, v40, v41
	s_nop 0
	v_cvt_pk_bf16_f32 v41, v42, v43
	global_store_dwordx2 v[46:47], v[40:41], off offset:3584
	s_and_b64 exec, exec, s[6:7]
	s_cbranch_execz .LBB0_134
	v_lshlrev_b64 v[30:31], 10, v[30:31]
	v_lshl_add_u64 v[30:31], s[4:5], 0, v[30:31]
	v_lshl_add_u64 v[30:31], v[30:31], 0, v[24:25]
	v_add_co_u32_e32 v30, vcc, 0x26000000, v30
	s_nop 1
	v_addc_co_u32_e32 v31, vcc, 0, v31, vcc
	global_store_dwordx2 v[30:31], v[84:85], off offset:896
	s_branch .LBB0_134
